# body-1 tail: vmcnt wait and the five K/V LDS writes issued before all 16 trailing exps (was 6 exps before the wait)
# baseline (speedup 1.0000x reference)
; template <bool START>
; __device__ __forceinline__ void partialSM(f32x16& p0, f32x16& p1, float& mhat, f32x16& negm, float& alpha) {
;     ...
;   for (int r = 0; r < 16; ++r) p0[r] = __builtin_amdgcn_exp2f(p0[r]);
; }
; __device__ __forceinline__ void finishSM(f32x16& p0, f32x16& p1, float alpha, float& l_reg, bf16x8& pa0, bf16x8& pa1, bf16x8& pa2, bf16x8& pa3) {
; #pragma unroll
;   for (int r = 0; r < 16; ++r) p1[r] = __builtin_amdgcn_exp2f(p1[r]);
;   float ps = 0;
; #pragma unroll
;   for (int r = 0; r < 16; ++r) ps += p0[r];
; #pragma unroll
;   for (int r = 0; r < 16; ++r) ps += p1[r];
;   { auto rr = __builtin_amdgcn_permlane32_swap(__float_as_uint(ps), __float_as_uint(ps), false, false);
;     ps = __uint_as_float(rr[0]) + __uint_as_float(rr[1]); }
;   l_reg = l_reg * alpha + ps;
; __device__ __forceinline__ void qkt(f32x16& p0, f32x16& p1, const char* Kn, const char* Kr, const char* Qr, const bf16x8* qr, const f32x16& negm, int lane) {
;   const int kn = (int)(uintptr_t)Kn + (lane & 31) * 16 + (lane >> 5) * 1024, kr = (int)(uintptr_t)Kr + (lane & 31) * 16 + (lane >> 5) * 1024, qa = (int)(uintptr_t)Qr + lane * 16;
;   bf16x8 a0, a1, b0, b1, qa_, qb_;
;     ...
;   a0 = dsr128<0 * 2048>(kn); a1 = dsr128<0 * 2048 + 512>(kn);
;   b0 = dsr128<1 * 2048>(kn); b1 = dsr128<1 * 2048 + 512>(kn); LGKM_W2(2, a0, a1);
;   p0 = __builtin_amdgcn_mfma_f32_32x32x16_bf16(a0, qr[0], negm, 0, 0, 0); p1 = __builtin_amdgcn_mfma_f32_32x32x16_bf16(a1, qr[0], negm, 0, 0, 0);
;   a0 = dsr128<2 * 2048>(kn); a1 = dsr128<2 * 2048 + 512>(kn); LGKM_W2(2, b0, b1); MM(b0, b1, qr[1]);
;   b0 = dsr128<3 * 2048>(kn); b1 = dsr128<3 * 2048 + 512>(kn); LGKM_W2(2, a0, a1); MM(a0, a1, qr[2]);
;   a0 = dsr128<4 * 2048>(kn); a1 = dsr128<4 * 2048 + 512>(kn); LGKM_W2(2, b0, b1); MM(b0, b1, qr[3]);
;   b0 = dsr128<5 * 2048>(kn); b1 = dsr128<5 * 2048 + 512>(kn); LGKM_W2(2, a0, a1); MM(a0, a1, qr[4]);
;   a0 = dsr128<6 * 2048>(kn); a1 = dsr128<6 * 2048 + 512>(kn); LGKM_W2(2, b0, b1); MM(b0, b1, qr[5]);
;   b0 = dsr128<7 * 2048>(kn); b1 = dsr128<7 * 2048 + 512>(kn); LGKM_W2(2, a0, a1); MM(a0, a1, qr[6]);
;   a0 = dsr128<0 * 2048>(kr); a1 = dsr128<0 * 2048 + 512>(kr); qa_ = dsr128<0 * 1024>(qa); LGKM_W2(3, b0, b1); MM(b0, b1, qr[7]);
;   b0 = dsr128<1 * 2048>(kr); b1 = dsr128<1 * 2048 + 512>(kr); qb_ = dsr128<1 * 1024>(qa); LGKM_W3(3, a0, a1, qa_); MM(a0, a1, qa_);
.LBB0_563:
	s_lshl_b64 vcc, s[0:1], 9
	s_waitcnt vmcnt(0)
	ds_write_b128 v197, v[162:165] offset:32768
	ds_write_b128 v197, v[166:169] offset:40960
	ds_write_b128 v200, v[170:173]
	ds_write_b128 v198, v[82:85] offset:16384
	ds_write_b128 v199, v[86:89] offset:16384
	v_exp_f32_e32 v230, v114
	v_exp_f32_e32 v231, v115
	v_exp_f32_e32 v232, v116
	v_exp_f32_e32 v233, v117
	v_exp_f32_e32 v234, v118
	v_exp_f32_e32 v235, v119
	v_exp_f32_e32 v236, v120
	v_exp_f32_e32 v237, v121
	v_exp_f32_e32 v238, v122
	v_exp_f32_e32 v239, v123
	v_exp_f32_e32 v240, v124
	v_exp_f32_e32 v241, v125
	v_exp_f32_e32 v242, v126
	v_exp_f32_e32 v243, v127
	v_exp_f32_e32 v244, v128
	v_exp_f32_e32 v245, v129
	s_waitcnt lgkmcnt(0)
	s_barrier
	ds_read_b128 v[82:85], v187 offset:0
	ds_read_b128 v[174:177], v187 offset:0x200
	ds_read_b128 v[178:181], v187 offset:0x800
	ds_read_b128 v[214:217], v187 offset:0xa00
	v_exp_f32_e32 v98, v98
	s_waitcnt lgkmcnt(2)
	v_exp_f32_e32 v99, v99
	v_mfma_f32_32x32x16_bf16 v[114:129], v[82:85], v[130:133], v[66:81]
	v_exp_f32_e32 v100, v100
	v_exp_f32_e32 v101, v101
	v_exp_f32_e32 v102, v102
	v_exp_f32_e32 v103, v103
	v_exp_f32_e32 v104, v104
	v_exp_f32_e32 v105, v105
	v_mfma_f32_32x32x16_bf16 v[82:97], v[174:177], v[130:133], v[66:81]
	v_exp_f32_e32 v106, v106
	ds_read_b128 v[174:177], v187 offset:0x1000
	ds_read_b128 v[218:221], v187 offset:0x1200
	s_waitcnt lgkmcnt(2)
	s_nop 0
	v_mfma_f32_32x32x16_bf16 v[114:129], v[178:181], v[134:137], v[114:129]
	v_add_f32_e32 v251, 0, v230
	v_add_f32_e32 v251, v231, v251
	v_add_f32_e32 v251, v232, v251
	ds_read_b128 v[178:181], v187 offset:0x1800
	v_mfma_f32_32x32x16_bf16 v[82:97], v[214:217], v[134:137], v[82:97]
	v_add_f32_e32 v251, v233, v251
	ds_read_b128 v[214:217], v187 offset:0x1a00
	s_waitcnt lgkmcnt(2)
	s_nop 0
	v_mfma_f32_32x32x16_bf16 v[114:129], v[174:177], v[138:141], v[114:129]
	v_exp_f32_e32 v107, v107
	v_add_f32_e32 v251, v234, v251
	v_add_f32_e32 v251, v235, v251
	ds_read_b128 v[174:177], v187 offset:0x2000
	v_mfma_f32_32x32x16_bf16 v[82:97], v[218:221], v[138:141], v[82:97]
	v_add_f32_e32 v251, v236, v251
	v_add_f32_e32 v251, v237, v251
	ds_read_b128 v[218:221], v187 offset:0x2200
	s_waitcnt lgkmcnt(2)
	s_nop 0
	v_mfma_f32_32x32x16_bf16 v[114:129], v[178:181], v[142:145], v[114:129]
	v_exp_f32_e32 v108, v108
	v_add_f32_e32 v251, v238, v251
	ds_read_b128 v[178:181], v187 offset:0x2800
	v_mfma_f32_32x32x16_bf16 v[82:97], v[214:217], v[142:145], v[82:97]
	v_add_f32_e32 v251, v239, v251
	v_add_f32_e32 v251, v240, v251
	ds_read_b128 v[214:217], v187 offset:0x2a00
	s_waitcnt lgkmcnt(2)
	s_nop 0
	v_mfma_f32_32x32x16_bf16 v[114:129], v[174:177], v[146:149], v[114:129]
	v_add_f32_e32 v251, v241, v251
	v_exp_f32_e32 v109, v109
	ds_read_b128 v[174:177], v187 offset:0x3000
	v_mfma_f32_32x32x16_bf16 v[82:97], v[218:221], v[146:149], v[82:97]
	v_add_f32_e32 v251, v242, v251
	v_add_f32_e32 v251, v243, v251
	ds_read_b128 v[218:221], v187 offset:0x3200
	s_waitcnt lgkmcnt(2)
	s_nop 0
	v_mfma_f32_32x32x16_bf16 v[114:129], v[178:181], v[150:153], v[114:129]
	v_add_f32_e32 v251, v244, v251
	v_add_f32_e32 v251, v245, v251
	ds_read_b128 v[178:181], v187 offset:0x3800
	v_mfma_f32_32x32x16_bf16 v[82:97], v[214:217], v[150:153], v[82:97]
	v_exp_f32_e32 v110, v110
	v_add_f32_e32 v251, v98, v251
	ds_read_b128 v[214:217], v187 offset:0x3a00
	s_waitcnt lgkmcnt(2)
	s_nop 0
	v_mfma_f32_32x32x16_bf16 v[114:129], v[174:177], v[154:157], v[114:129]
	v_add_f32_e32 v251, v99, v251
	v_add_f32_e32 v251, v100, v251
	v_add_f32_e32 v251, v101, v251
	ds_read_b128 v[174:177], v203 offset:0
	v_mfma_f32_32x32x16_bf16 v[82:97], v[218:221], v[154:157], v[82:97]
	v_exp_f32_e32 v111, v111
	v_add_f32_e32 v251, v102, v251
	ds_read_b128 v[218:221], v203 offset:0x200
	ds_read_b128 v[222:225], v189 offset:0
	s_waitcnt lgkmcnt(3)
	s_nop 0
	v_mfma_f32_32x32x16_bf16 v[114:129], v[178:181], v[158:161], v[114:129]
	v_add_f32_e32 v251, v103, v251
	v_add_f32_e32 v251, v104, v251
	ds_read_b128 v[178:181], v203 offset:0x800
	v_mfma_f32_32x32x16_bf16 v[82:97], v[214:217], v[158:161], v[82:97]
	v_add_f32_e32 v251, v105, v251
	v_exp_f32_e32 v112, v112
	ds_read_b128 v[214:217], v203 offset:0xa00
	ds_read_b128 v[226:229], v189 offset:0x400
	s_waitcnt lgkmcnt(3)
	s_nop 0
	v_mfma_f32_32x32x16_bf16 v[114:129], v[174:177], v[222:225], v[114:129]
	v_add_f32_e32 v251, v106, v251
	v_add_f32_e32 v251, v107, v251
	ds_read_b128 v[174:177], v203 offset:0x1000
	v_mfma_f32_32x32x16_bf16 v[82:97], v[218:221], v[222:225], v[82:97]
	v_add_f32_e32 v251, v108, v251
	v_add_f32_e32 v251, v109, v251
	ds_read_b128 v[218:221], v203 offset:0x1200
	ds_read_b128 v[222:225], v189 offset:0x800
	s_waitcnt lgkmcnt(3)
	s_nop 0
	v_mfma_f32_32x32x16_bf16 v[114:129], v[178:181], v[226:229], v[114:129]
	v_exp_f32_e32 v113, v113
	v_add_f32_e32 v251, v110, v251
	ds_read_b128 v[178:181], v203 offset:0x1800
	v_mfma_f32_32x32x16_bf16 v[82:97], v[214:217], v[226:229], v[82:97]
	v_add_f32_e32 v251, v111, v251
	v_add_f32_e32 v251, v112, v251
	v_add_f32_e32 v251, v113, v251
	ds_read_b128 v[214:217], v203 offset:0x1a00
	ds_read_b128 v[226:229], v189 offset:0xc00
	s_waitcnt lgkmcnt(3)
	s_nop 0
	s_waitcnt lgkmcnt(0)
	v_mfma_f32_32x32x16_bf16 v[114:129], v[174:177], v[222:225], v[114:129]
	v_mfma_f32_32x32x16_bf16 v[114:129], v[178:181], v[226:229], v[114:129]
	v_cvt_pk_bf16_f32 v178, v106, v107
	v_cvt_pk_bf16_f32 v179, v108, v109
	v_cvt_pk_bf16_f32 v180, v110, v111
	v_cvt_pk_bf16_f32 v181, v112, v113
	v_cvt_pk_bf16_f32 v106, v230, v231
	v_cvt_pk_bf16_f32 v107, v232, v233
	v_cvt_pk_bf16_f32 v108, v234, v235
	v_mfma_f32_32x32x16_bf16 v[82:97], v[218:221], v[222:225], v[82:97]
	v_cvt_pk_bf16_f32 v109, v236, v237
	v_cvt_pk_bf16_f32 v110, v238, v239
	v_cvt_pk_bf16_f32 v111, v240, v241
	v_cvt_pk_bf16_f32 v112, v242, v243
	v_cvt_pk_bf16_f32 v113, v244, v245
	v_cvt_pk_bf16_f32 v174, v98, v99
	v_cvt_pk_bf16_f32 v175, v100, v101
	v_mfma_f32_32x32x16_bf16 v[82:97], v[214:217], v[226:229], v[82:97]
	v_cvt_pk_bf16_f32 v176, v102, v103
	v_cvt_pk_bf16_f32 v177, v104, v105
	v_mov_b32_e32 v213, v251
	v_mov_b32_e32 v214, v251
	s_nop 1
	v_permlane32_swap_b32_e32 v213, v214
	v_permlane32_swap_b32_e32 v106, v108
	v_permlane32_swap_b32_e32 v107, v109
	v_permlane32_swap_b32_e32 v110, v112
	v_permlane32_swap_b32_e32 v111, v113
	v_permlane32_swap_b32_e32 v174, v176
	v_permlane32_swap_b32_e32 v175, v177
	v_permlane32_swap_b32_e32 v178, v180
	v_permlane32_swap_b32_e32 v179, v181
	s_cmp_lt_u32 s83, s94
	s_cselect_b64 s[0:1], -1, 0
	s_cmp_ge_u32 s83, s94
	s_cbranch_scc1 .LBB0_565
	s_ashr_i32 s77, s76, 31
	s_lshl_b64 s[84:85], s[76:77], 10
	s_lshl_b64 s[86:87], s[76:77], 7
	v_lshl_add_u64 v[98:99], v[192:193], 0, s[84:85]
	global_load_dwordx4 v[162:165], v[98:99], off
	global_load_dwordx4 v[166:169], v[98:99], off offset:128
	v_lshl_add_u64 v[98:99], v[190:191], 0, s[86:87]
	global_load_dwordx4 v[170:173], v[98:99], off

; template <bool START>
; __device__ __forceinline__ void partialSM(f32x16& p0, f32x16& p1, float& mhat, f32x16& negm, float& alpha) {
;     ...
;   for (int r = 0; r < 16; ++r) p0[r] = __builtin_amdgcn_exp2f(p0[r]);
; }
; __device__ __forceinline__ void finishSM(f32x16& p0, f32x16& p1, float alpha, float& l_reg, bf16x8& pa0, bf16x8& pa1, bf16x8& pa2, bf16x8& pa3) {
; #pragma unroll
;   for (int r = 0; r < 16; ++r) p1[r] = __builtin_amdgcn_exp2f(p1[r]);
;   float ps = 0;
; #pragma unroll
;   for (int r = 0; r < 16; ++r) ps += p0[r];
; #pragma unroll
;   for (int r = 0; r < 16; ++r) ps += p1[r];
;   { auto rr = __builtin_amdgcn_permlane32_swap(__float_as_uint(ps), __float_as_uint(ps), false, false);
;     ps = __uint_as_float(rr[0]) + __uint_as_float(rr[1]); }
;   l_reg = l_reg * alpha + ps;
; __device__ __forceinline__ void qkt(f32x16& p0, f32x16& p1, const char* Kn, const char* Kr, const char* Qr, const bf16x8* qr, const f32x16& negm, int lane) {
;   const int kn = (int)(uintptr_t)Kn + (lane & 31) * 16 + (lane >> 5) * 1024, kr = (int)(uintptr_t)Kr + (lane & 31) * 16 + (lane >> 5) * 1024, qa = (int)(uintptr_t)Qr + lane * 16;
;   bf16x8 a0, a1, b0, b1, qa_, qb_;
;     ...
;   a0 = dsr128<0 * 2048>(kn); a1 = dsr128<0 * 2048 + 512>(kn);
;   b0 = dsr128<1 * 2048>(kn); b1 = dsr128<1 * 2048 + 512>(kn); LGKM_W2(2, a0, a1);
;   p0 = __builtin_amdgcn_mfma_f32_32x32x16_bf16(a0, qr[0], negm, 0, 0, 0); p1 = __builtin_amdgcn_mfma_f32_32x32x16_bf16(a1, qr[0], negm, 0, 0, 0);
;   a0 = dsr128<2 * 2048>(kn); a1 = dsr128<2 * 2048 + 512>(kn); LGKM_W2(2, b0, b1); MM(b0, b1, qr[1]);
;   b0 = dsr128<3 * 2048>(kn); b1 = dsr128<3 * 2048 + 512>(kn); LGKM_W2(2, a0, a1); MM(a0, a1, qr[2]);
;   a0 = dsr128<4 * 2048>(kn); a1 = dsr128<4 * 2048 + 512>(kn); LGKM_W2(2, b0, b1); MM(b0, b1, qr[3]);
;   b0 = dsr128<5 * 2048>(kn); b1 = dsr128<5 * 2048 + 512>(kn); LGKM_W2(2, a0, a1); MM(a0, a1, qr[4]);
;   a0 = dsr128<6 * 2048>(kn); a1 = dsr128<6 * 2048 + 512>(kn); LGKM_W2(2, b0, b1); MM(b0, b1, qr[5]);
;   b0 = dsr128<7 * 2048>(kn); b1 = dsr128<7 * 2048 + 512>(kn); LGKM_W2(2, a0, a1); MM(a0, a1, qr[6]);
;   a0 = dsr128<0 * 2048>(kr); a1 = dsr128<0 * 2048 + 512>(kr); qa_ = dsr128<0 * 1024>(qa); LGKM_W2(3, b0, b1); MM(b0, b1, qr[7]);
;   b0 = dsr128<1 * 2048>(kr); b1 = dsr128<1 * 2048 + 512>(kr); qb_ = dsr128<1 * 1024>(qa); LGKM_W3(3, a0, a1, qa_); MM(a0, a1, qa_);
.LBB0_1377:
	s_waitcnt vmcnt(0)
	ds_write_b128 v202, v[162:165] offset:32768
	ds_write_b128 v202, v[166:169] offset:40960
	ds_write_b128 v205, v[170:173]
	ds_write_b128 v203, v[82:85] offset:16384
	ds_write_b128 v204, v[86:89] offset:16384
	v_exp_f32_e32 v234, v114
	v_exp_f32_e32 v235, v115
	v_exp_f32_e32 v236, v116
	v_exp_f32_e32 v237, v117
	v_exp_f32_e32 v238, v118
	v_exp_f32_e32 v239, v119
	v_exp_f32_e32 v240, v120
	v_exp_f32_e32 v241, v121
	v_exp_f32_e32 v242, v122
	v_exp_f32_e32 v243, v123
	v_exp_f32_e32 v244, v124
	v_exp_f32_e32 v245, v125
	v_exp_f32_e32 v246, v126
	v_exp_f32_e32 v247, v127
	v_exp_f32_e32 v248, v128
	v_exp_f32_e32 v249, v129
	s_waitcnt lgkmcnt(0)
	s_barrier
	ds_read_b128 v[82:85], v208 offset:0
	ds_read_b128 v[174:177], v208 offset:0x200
	ds_read_b128 v[178:181], v208 offset:0x800
	ds_read_b128 v[218:221], v208 offset:0xa00
	v_exp_f32_e32 v98, v98
	s_waitcnt lgkmcnt(2)
	v_exp_f32_e32 v99, v99
	v_mfma_f32_32x32x16_bf16 v[114:129], v[82:85], v[130:133], v[66:81]
	v_exp_f32_e32 v100, v100
	v_exp_f32_e32 v101, v101
	v_exp_f32_e32 v102, v102
	v_exp_f32_e32 v103, v103
	v_exp_f32_e32 v104, v104
	v_exp_f32_e32 v105, v105
	v_mfma_f32_32x32x16_bf16 v[82:97], v[174:177], v[130:133], v[66:81]
	v_exp_f32_e32 v106, v106
	ds_read_b128 v[174:177], v208 offset:0x1000
	ds_read_b128 v[222:225], v208 offset:0x1200
	s_waitcnt lgkmcnt(2)
	s_nop 0
	v_mfma_f32_32x32x16_bf16 v[114:129], v[178:181], v[134:137], v[114:129]
	v_add_f32_e32 v251, 0, v234
	v_add_f32_e32 v251, v235, v251
	v_add_f32_e32 v251, v236, v251
	ds_read_b128 v[178:181], v208 offset:0x1800
	v_mfma_f32_32x32x16_bf16 v[82:97], v[218:221], v[134:137], v[82:97]
	v_add_f32_e32 v251, v237, v251
	ds_read_b128 v[218:221], v208 offset:0x1a00
	s_waitcnt lgkmcnt(2)
	s_nop 0
	v_mfma_f32_32x32x16_bf16 v[114:129], v[174:177], v[138:141], v[114:129]
	v_exp_f32_e32 v107, v107
	v_add_f32_e32 v251, v238, v251
	v_add_f32_e32 v251, v239, v251
	ds_read_b128 v[174:177], v208 offset:0x2000
	v_mfma_f32_32x32x16_bf16 v[82:97], v[222:225], v[138:141], v[82:97]
	v_add_f32_e32 v251, v240, v251
	v_add_f32_e32 v251, v241, v251
	ds_read_b128 v[222:225], v208 offset:0x2200
	s_waitcnt lgkmcnt(2)
	s_nop 0
	v_mfma_f32_32x32x16_bf16 v[114:129], v[178:181], v[142:145], v[114:129]
	v_exp_f32_e32 v108, v108
	v_add_f32_e32 v251, v242, v251
	ds_read_b128 v[178:181], v208 offset:0x2800
	v_mfma_f32_32x32x16_bf16 v[82:97], v[218:221], v[142:145], v[82:97]
	v_add_f32_e32 v251, v243, v251
	v_add_f32_e32 v251, v244, v251
	ds_read_b128 v[218:221], v208 offset:0x2a00
	s_waitcnt lgkmcnt(2)
	s_nop 0
	v_mfma_f32_32x32x16_bf16 v[114:129], v[174:177], v[146:149], v[114:129]
	v_add_f32_e32 v251, v245, v251
	v_exp_f32_e32 v109, v109
	ds_read_b128 v[174:177], v208 offset:0x3000
	v_mfma_f32_32x32x16_bf16 v[82:97], v[222:225], v[146:149], v[82:97]
	v_add_f32_e32 v251, v246, v251
	v_add_f32_e32 v251, v247, v251
	ds_read_b128 v[222:225], v208 offset:0x3200
	s_waitcnt lgkmcnt(2)
	s_nop 0
	v_mfma_f32_32x32x16_bf16 v[114:129], v[178:181], v[150:153], v[114:129]
	v_add_f32_e32 v251, v248, v251
	v_add_f32_e32 v251, v249, v251
	ds_read_b128 v[178:181], v208 offset:0x3800
	v_mfma_f32_32x32x16_bf16 v[82:97], v[218:221], v[150:153], v[82:97]
	v_exp_f32_e32 v110, v110
	v_add_f32_e32 v251, v98, v251
	ds_read_b128 v[218:221], v208 offset:0x3a00
	s_waitcnt lgkmcnt(2)
	s_nop 0
	v_mfma_f32_32x32x16_bf16 v[114:129], v[174:177], v[154:157], v[114:129]
	v_add_f32_e32 v251, v99, v251
	v_add_f32_e32 v251, v100, v251
	v_add_f32_e32 v251, v101, v251
	ds_read_b128 v[174:177], v209 offset:0
	v_mfma_f32_32x32x16_bf16 v[82:97], v[222:225], v[154:157], v[82:97]
	v_exp_f32_e32 v111, v111
	v_add_f32_e32 v251, v102, v251
	ds_read_b128 v[222:225], v209 offset:0x200
	ds_read_b128 v[226:229], v201 offset:0
	s_waitcnt lgkmcnt(3)
	s_nop 0
	v_mfma_f32_32x32x16_bf16 v[114:129], v[178:181], v[158:161], v[114:129]
	v_add_f32_e32 v251, v103, v251
	v_add_f32_e32 v251, v104, v251
	ds_read_b128 v[178:181], v209 offset:0x800
	v_mfma_f32_32x32x16_bf16 v[82:97], v[218:221], v[158:161], v[82:97]
	v_add_f32_e32 v251, v105, v251
	v_exp_f32_e32 v112, v112
	ds_read_b128 v[218:221], v209 offset:0xa00
	ds_read_b128 v[230:233], v201 offset:0x400
	s_waitcnt lgkmcnt(3)
	s_nop 0
	v_mfma_f32_32x32x16_bf16 v[114:129], v[174:177], v[226:229], v[114:129]
	v_add_f32_e32 v251, v106, v251
	v_add_f32_e32 v251, v107, v251
	ds_read_b128 v[174:177], v209 offset:0x1000
	v_mfma_f32_32x32x16_bf16 v[82:97], v[222:225], v[226:229], v[82:97]
	v_add_f32_e32 v251, v108, v251
	v_add_f32_e32 v251, v109, v251
	ds_read_b128 v[222:225], v209 offset:0x1200
	ds_read_b128 v[226:229], v201 offset:0x800
	s_waitcnt lgkmcnt(3)
	s_nop 0
	v_mfma_f32_32x32x16_bf16 v[114:129], v[178:181], v[230:233], v[114:129]
	v_exp_f32_e32 v113, v113
	v_add_f32_e32 v251, v110, v251
	ds_read_b128 v[178:181], v209 offset:0x1800
	v_mfma_f32_32x32x16_bf16 v[82:97], v[218:221], v[230:233], v[82:97]
	v_add_f32_e32 v251, v111, v251
	v_add_f32_e32 v251, v112, v251
	v_add_f32_e32 v251, v113, v251
	ds_read_b128 v[218:221], v209 offset:0x1a00
	ds_read_b128 v[230:233], v201 offset:0xc00
	s_waitcnt lgkmcnt(3)
	s_nop 0
	s_waitcnt lgkmcnt(0)
	v_mfma_f32_32x32x16_bf16 v[114:129], v[174:177], v[226:229], v[114:129]
	v_mfma_f32_32x32x16_bf16 v[114:129], v[178:181], v[230:233], v[114:129]
	v_cvt_pk_bf16_f32 v178, v106, v107
	v_cvt_pk_bf16_f32 v179, v108, v109
	v_cvt_pk_bf16_f32 v180, v110, v111
	v_cvt_pk_bf16_f32 v181, v112, v113
	v_cvt_pk_bf16_f32 v106, v234, v235
	v_cvt_pk_bf16_f32 v107, v236, v237
	v_cvt_pk_bf16_f32 v108, v238, v239
	v_mfma_f32_32x32x16_bf16 v[82:97], v[222:225], v[226:229], v[82:97]
	v_cvt_pk_bf16_f32 v109, v240, v241
	v_cvt_pk_bf16_f32 v110, v242, v243
	v_cvt_pk_bf16_f32 v111, v244, v245
	v_cvt_pk_bf16_f32 v112, v246, v247
	v_cvt_pk_bf16_f32 v113, v248, v249
	v_cvt_pk_bf16_f32 v174, v98, v99
	v_cvt_pk_bf16_f32 v175, v100, v101
	v_mfma_f32_32x32x16_bf16 v[82:97], v[218:221], v[230:233], v[82:97]
	v_cvt_pk_bf16_f32 v176, v102, v103
	v_cvt_pk_bf16_f32 v177, v104, v105
	v_mov_b32_e32 v218, v251
	v_mov_b32_e32 v219, v251
	s_nop 1
	v_permlane32_swap_b32_e32 v218, v219
	v_permlane32_swap_b32_e32 v106, v108
	v_permlane32_swap_b32_e32 v107, v109
	v_permlane32_swap_b32_e32 v110, v112
	v_permlane32_swap_b32_e32 v111, v113
	v_permlane32_swap_b32_e32 v174, v176
	v_permlane32_swap_b32_e32 v175, v177
	v_permlane32_swap_b32_e32 v178, v180
	v_permlane32_swap_b32_e32 v179, v181
	s_cmp_lt_u32 s91, s96
	s_cselect_b64 s[0:1], -1, 0
	s_cmp_ge_u32 s91, s96
	s_cbranch_scc1 .LBB0_1379
	v_add_co_u32_e32 v98, vcc, 0x60f0000, v196
	s_nop 1
	v_addc_co_u32_e32 v99, vcc, 0, v197, vcc
	global_load_dwordx4 v[162:165], v[98:99], off
	global_load_dwordx4 v[166:169], v[98:99], off offset:128
	v_add_co_u32_e32 v98, vcc, 0xe1c6000, v194
	s_nop 1
	v_addc_co_u32_e32 v99, vcc, 0, v195, vcc
	global_load_dwordx4 v[170:173], v[98:99], off
